# MLA prompt loop: one static s_setprio 1 at entry for wave group B (waves 4-7), reset before the epilogue
# baseline (speedup 1.0000x reference)
.Lmy_tf_28:
.Lmy_te_30:
	s_setprio 0
	s_nop 15
	s_nop 3
	s_mov_b64 s[14:15], -1
	s_branch .LBB0_1101
.Lmy_B_entry:
	s_setprio 1
	s_mov_b32 s30, 0x20000
	s_mov_b32 s31, 0
	s_mov_b32 s12, 0x1000
	s_mov_b32 s13, 0
	s_lshr_b32 s71, s24, 1
	s_lshr_b32 s79, s25, 2
	s_add_i32 s79, s79, -1
	s_mov_b32 s0, 0x80000
	s_mov_b32 s1, 0
	v_lshl_add_u64 v[24:25], v[16:17], 0, s[0:1]
	s_mov_b32 s0, 0x60000
	v_lshl_add_u64 v[28:29], v[224:225], 0, s[0:1]
	s_mov_b32 s0, 0x4000
	v_lshl_add_u64 v[30:31], v[222:223], 0, s[0:1]
	s_waitcnt lgkmcnt(0)
	v_mfma_f32_32x32x16_bf16 v[82:97], v[218:221], v[4:7], v[66:81]
	v_mfma_f32_32x32x16_bf16 v[98:113], v[214:217], v[4:7], v[66:81]
	v_mfma_f32_32x32x16_bf16 v[82:97], v[210:213], v[8:11], v[82:97]
	v_mfma_f32_32x32x16_bf16 v[98:113], v[206:209], v[8:11], v[98:113]
	v_mfma_f32_32x32x16_bf16 v[82:97], v[202:205], v[12:15], v[82:97]
	v_mfma_f32_32x32x16_bf16 v[98:113], v[198:201], v[12:15], v[98:113]
	v_mfma_f32_32x32x16_bf16 v[82:97], v[194:197], v[130:133], v[82:97]
	v_mfma_f32_32x32x16_bf16 v[98:113], v[190:193], v[130:133], v[98:113]
	v_mfma_f32_32x32x16_bf16 v[82:97], v[186:189], v[134:137], v[82:97]
	v_mfma_f32_32x32x16_bf16 v[98:113], v[182:185], v[134:137], v[98:113]
	v_mfma_f32_32x32x16_bf16 v[82:97], v[178:181], v[138:141], v[82:97]
	v_mfma_f32_32x32x16_bf16 v[98:113], v[174:177], v[138:141], v[98:113]
	v_add_u32_e32 v2, 0x3000, v238
	ds_read_b128 v[218:221], v2
	ds_read_b128 v[214:217], v2 offset:512
	ds_read_b128 v[210:213], v2 offset:2048
	ds_read_b128 v[206:209], v2 offset:2560
	ds_read_b128 v[202:205], v2 offset:4096
	ds_read_b128 v[198:201], v2 offset:4608
	ds_read_b128 v[194:197], v2 offset:6144
	ds_read_b128 v[190:193], v2 offset:6656
	ds_read_b128 v[186:189], v2 offset:8192
	ds_read_b128 v[182:185], v2 offset:8704
	ds_read_b128 v[178:181], v2 offset:10240
	ds_read_b128 v[174:177], v2 offset:10752
	s_nop 7
	v_max3_f32 v19, v82, v83, v84
	v_max3_f32 v26, v85, v86, v87
	v_max3_f32 v19, v19, v88, v89
	v_max3_f32 v26, v26, v90, v91
	v_max3_f32 v19, v19, v92, v93
	v_max3_f32 v26, v26, v94, v95
	v_max3_f32 v19, v19, v96, v97
	v_max3_f32 v26, v26, v98, v99
	v_max3_f32 v19, v19, v100, v101
	v_max3_f32 v26, v26, v102, v103
	v_max3_f32 v19, v19, v104, v105
	v_max3_f32 v26, v26, v106, v107
	v_max3_f32 v19, v19, v108, v109
	v_max3_f32 v26, v26, v110, v111
	v_max3_f32 v19, v19, v112, v113
	v_max_f32_e32 v19, v19, v26
	v_mov_b32_e32 v26, v19
	s_nop 1
	v_permlane32_swap_b32_e32 v19, v26
	v_max_f32_e32 v19, v19, v26
	v_max_f32_e32 v19, v19, v19
	v_mov_b32_e32 v239, v19
	v_xor_b32_e32 v66, 0x80000000, v19
	v_mov_b32_e32 v67, v66
	v_mov_b32_e32 v68, v66
	v_mov_b32_e32 v69, v66
	v_mov_b32_e32 v70, v66
	v_mov_b32_e32 v71, v66
	v_mov_b32_e32 v72, v66
	v_mov_b32_e32 v73, v66
	v_mov_b32_e32 v74, v66
	v_mov_b32_e32 v75, v66
	v_mov_b32_e32 v76, v66
	v_mov_b32_e32 v77, v66
	v_mov_b32_e32 v78, v66
	v_mov_b32_e32 v79, v66
	v_mov_b32_e32 v80, v66
	v_mov_b32_e32 v81, v66
	v_sub_f32_e32 v82, v82, v19
	v_sub_f32_e32 v83, v83, v19
	v_sub_f32_e32 v84, v84, v19
	v_sub_f32_e32 v85, v85, v19
	v_sub_f32_e32 v86, v86, v19
	v_sub_f32_e32 v87, v87, v19
	v_sub_f32_e32 v88, v88, v19
	v_sub_f32_e32 v89, v89, v19
	v_sub_f32_e32 v90, v90, v19
	v_sub_f32_e32 v91, v91, v19
	v_sub_f32_e32 v92, v92, v19
	v_sub_f32_e32 v93, v93, v19
	v_sub_f32_e32 v94, v94, v19
	v_sub_f32_e32 v95, v95, v19
	v_sub_f32_e32 v96, v96, v19
	v_sub_f32_e32 v97, v97, v19
	v_sub_f32_e32 v98, v98, v19
	v_sub_f32_e32 v99, v99, v19
	v_sub_f32_e32 v100, v100, v19
	v_sub_f32_e32 v101, v101, v19
	v_sub_f32_e32 v102, v102, v19
	v_sub_f32_e32 v103, v103, v19
	v_sub_f32_e32 v104, v104, v19
	v_sub_f32_e32 v105, v105, v19
	v_sub_f32_e32 v106, v106, v19
	v_sub_f32_e32 v107, v107, v19
	v_sub_f32_e32 v108, v108, v19
	v_sub_f32_e32 v109, v109, v19
	v_sub_f32_e32 v110, v110, v19
	v_sub_f32_e32 v111, v111, v19
	v_sub_f32_e32 v112, v112, v19
	v_sub_f32_e32 v113, v113, v19
	s_cmp_lt_i32 s79, 1
	s_cbranch_scc1 .Lmy_B_tail
	s_waitcnt lgkmcnt(0)
	v_mov_b32_e32 v2, v237
	v_mfma_f32_32x32x16_bf16 v[142:157], v[218:221], v[4:7], v[66:81]
	v_exp_f32_e32 v82, v82
	v_exp_f32_e32 v83, v83
	v_exp_f32_e32 v84, v84
	v_add_f32_e32 v27, v82, v83
	v_exp_f32_e32 v85, v85
	ds_read_b64_tr_b16 v[114:115], v2 offset:49152
	ds_read_b64_tr_b16 v[116:117], v2 offset:49664
	ds_read_b64_tr_b16 v[118:119], v2 offset:50176
	ds_read_b64_tr_b16 v[120:121], v2 offset:50688
	v_mfma_f32_32x32x16_bf16 v[158:173], v[214:217], v[4:7], v[66:81]
	v_exp_f32_e32 v86, v86
	v_add_f32_e32 v27, v27, v84
	v_exp_f32_e32 v87, v87
	v_add_f32_e32 v27, v27, v85
	v_exp_f32_e32 v88, v88
	ds_read_b64_tr_b16 v[122:123], v2 offset:51200
	ds_read_b64_tr_b16 v[124:125], v2 offset:51712
	ds_read_b64_tr_b16 v[126:127], v2 offset:52224
	ds_read_b64_tr_b16 v[128:129], v2 offset:52736
	v_mfma_f32_32x32x16_bf16 v[142:157], v[210:213], v[8:11], v[142:157]
	v_add_f32_e32 v27, v27, v86
	v_exp_f32_e32 v89, v89
	v_add_f32_e32 v27, v27, v87
	v_add_f32_e32 v27, v27, v88
	v_add_f32_e32 v27, v27, v89
	ds_read_b64_tr_b16 v[240:241], v2 offset:53248
	ds_read_b64_tr_b16 v[242:243], v2 offset:53760
	ds_read_b64_tr_b16 v[244:245], v2 offset:54272
	ds_read_b64_tr_b16 v[246:247], v2 offset:54784
	v_mfma_f32_32x32x16_bf16 v[158:173], v[206:209], v[8:11], v[158:173]
	v_cvt_pk_bf16_f32 v82, v82, v83
	v_cvt_pk_bf16_f32 v83, v84, v85
	v_cvt_pk_bf16_f32 v84, v86, v87
	v_cvt_pk_bf16_f32 v85, v88, v89
	ds_read_b64_tr_b16 v[248:249], v2 offset:55296
	ds_read_b64_tr_b16 v[250:251], v2 offset:55808
	ds_read_b64_tr_b16 v[20:21], v2 offset:56320
	ds_read_b64_tr_b16 v[22:23], v2 offset:56832
	v_mfma_f32_32x32x16_bf16 v[142:157], v[202:205], v[12:15], v[142:157]
	v_exp_f32_e32 v90, v90
	v_exp_f32_e32 v91, v91
	v_exp_f32_e32 v92, v92
	v_add_f32_e32 v27, v27, v90
	v_exp_f32_e32 v93, v93
	v_mfma_f32_32x32x16_bf16 v[158:173], v[198:201], v[12:15], v[158:173]
	v_add_f32_e32 v27, v27, v91
	v_exp_f32_e32 v94, v94
	v_add_f32_e32 v27, v27, v92
	v_exp_f32_e32 v95, v95
	v_add_f32_e32 v27, v27, v93
	s_waitcnt vmcnt(2)
	s_barrier
	v_mfma_f32_32x32x16_bf16 v[142:157], v[194:197], v[130:133], v[142:157]
	s_add_u32 m0, s57, 0x6000
	v_exp_f32_e32 v96, v96
	v_add_f32_e32 v27, v27, v94
	global_load_lds_dwordx4 v[28:29], off
	v_lshl_add_u64 v[28:29], v[28:29], 0, s[30:31]
	v_exp_f32_e32 v97, v97
	v_add_f32_e32 v27, v27, v95
	v_add_f32_e32 v27, v27, v96
	v_mfma_f32_32x32x16_bf16 v[158:173], v[190:193], v[130:133], v[158:173]
	s_add_u32 m0, s40, 0x0
	v_add_f32_e32 v27, v27, v97
	v_cvt_pk_bf16_f32 v90, v90, v91
	global_load_lds_dwordx4 v[24:25], off
	v_lshl_add_u64 v[24:25], v[24:25], 0, s[30:31]
	v_cvt_pk_bf16_f32 v91, v92, v93
	v_cvt_pk_bf16_f32 v92, v94, v95
	v_cvt_pk_bf16_f32 v93, v96, v97
	v_mfma_f32_32x32x16_bf16 v[142:157], v[186:189], v[134:137], v[142:157]
	s_add_u32 m0, s40, 0x3000
	v_exp_f32_e32 v98, v98
	v_exp_f32_e32 v99, v99
	global_load_lds_dwordx4 v[24:25], off
	v_lshl_add_u64 v[24:25], v[24:25], 0, s[30:31]
	v_exp_f32_e32 v100, v100
	v_add_f32_e32 v27, v27, v98
	v_exp_f32_e32 v101, v101
	v_mfma_f32_32x32x16_bf16 v[158:173], v[182:185], v[134:137], v[158:173]
	v_add_f32_e32 v27, v27, v99
	v_exp_f32_e32 v102, v102
	v_add_f32_e32 v27, v27, v100
	v_exp_f32_e32 v103, v103
	v_add_f32_e32 v27, v27, v101
	v_mfma_f32_32x32x16_bf16 v[142:157], v[178:181], v[138:141], v[142:157]
	v_exp_f32_e32 v104, v104
	v_add_f32_e32 v27, v27, v102
	v_exp_f32_e32 v105, v105
	v_add_f32_e32 v27, v27, v103
	v_add_f32_e32 v27, v27, v104
	v_mfma_f32_32x32x16_bf16 v[158:173], v[174:177], v[138:141], v[158:173]
	v_add_f32_e32 v27, v27, v105
	v_cvt_pk_bf16_f32 v98, v98, v99
	v_cvt_pk_bf16_f32 v99, v100, v101
	v_cvt_pk_bf16_f32 v100, v102, v103
	v_cvt_pk_bf16_f32 v101, v104, v105
	s_waitcnt lgkmcnt(0)
	v_add_u32_e32 v2, 0x6000, v238
	v_mfma_f32_32x32x16_bf16 v[34:49], v[82:85], v[114:117], v[34:49]
	v_exp_f32_e32 v106, v106
	v_exp_f32_e32 v107, v107
	v_exp_f32_e32 v108, v108
	v_add_f32_e32 v27, v27, v106
	v_exp_f32_e32 v109, v109
	ds_read_b128 v[218:221], v2
	ds_read_b128 v[214:217], v2 offset:512
	ds_read_b128 v[210:213], v2 offset:2048
	v_mfma_f32_32x32x16_bf16 v[50:65], v[82:85], v[240:243], v[50:65]
	v_add_f32_e32 v27, v27, v107
	v_exp_f32_e32 v110, v110
	v_add_f32_e32 v27, v27, v108
	v_exp_f32_e32 v111, v111
	v_add_f32_e32 v27, v27, v109
	ds_read_b128 v[206:209], v2 offset:2560
	ds_read_b128 v[202:205], v2 offset:4096
	ds_read_b128 v[198:201], v2 offset:4608
	v_mfma_f32_32x32x16_bf16 v[34:49], v[90:93], v[118:121], v[34:49]
	v_exp_f32_e32 v112, v112
	v_add_f32_e32 v27, v27, v110
	v_exp_f32_e32 v113, v113
	v_add_f32_e32 v27, v27, v111
	v_add_f32_e32 v27, v27, v112
	ds_read_b128 v[194:197], v2 offset:6144
	ds_read_b128 v[190:193], v2 offset:6656
	ds_read_b128 v[186:189], v2 offset:8192
	v_mfma_f32_32x32x16_bf16 v[50:65], v[90:93], v[244:247], v[50:65]
	v_add_f32_e32 v27, v27, v113
	v_cvt_pk_bf16_f32 v106, v106, v107
	v_cvt_pk_bf16_f32 v107, v108, v109
	v_cvt_pk_bf16_f32 v108, v110, v111
	v_cvt_pk_bf16_f32 v109, v112, v113
	v_add_f32_e32 v236, v236, v27
	ds_read_b128 v[182:185], v2 offset:8704
	ds_read_b128 v[178:181], v2 offset:10240
	ds_read_b128 v[174:177], v2 offset:10752
	v_mfma_f32_32x32x16_bf16 v[34:49], v[98:101], v[122:125], v[34:49]
	v_max3_f32 v19, v142, v143, v144
	v_max3_f32 v26, v145, v146, v147
	v_max3_f32 v19, v19, v148, v149
	v_max3_f32 v26, v26, v150, v151
	v_mfma_f32_32x32x16_bf16 v[50:65], v[98:101], v[248:251], v[50:65]
	v_max3_f32 v19, v19, v152, v153
	v_max3_f32 v26, v26, v154, v155
	v_max3_f32 v19, v19, v156, v157
	v_max3_f32 v26, v26, v158, v159
	v_mfma_f32_32x32x16_bf16 v[34:49], v[106:109], v[126:129], v[34:49]
	v_max3_f32 v19, v19, v160, v161
	v_max3_f32 v26, v26, v162, v163
	v_max3_f32 v19, v19, v164, v165
	v_max3_f32 v26, v26, v166, v167
	v_mfma_f32_32x32x16_bf16 v[50:65], v[106:109], v[20:23], v[50:65]
	v_max3_f32 v19, v19, v168, v169
	v_max3_f32 v26, v26, v170, v171
	v_max3_f32 v19, v19, v172, v173
	v_max_f32_e32 v19, v19, v26
	v_cmp_lt_f32_e32 vcc, s41, v19
	s_cbranch_vccz .Lmy_nors_31
	s_nop 15
	s_nop 15
	v_mov_b32_e32 v26, v19
	s_nop 1
	v_permlane32_swap_b32_e32 v19, v26
	v_max_f32_e32 v19, v19, v26
	v_max_f32_e32 v19, v19, v19
	v_max_f32_e32 v90, 0, v19
	v_exp_f32_e64 v91, -v90
	v_add_f32_e32 v239, v239, v90
	v_xor_b32_e32 v66, 0x80000000, v239
	v_mov_b32_e32 v67, v66
	v_mov_b32_e32 v68, v66
	v_mov_b32_e32 v69, v66
	v_mov_b32_e32 v70, v66
	v_mov_b32_e32 v71, v66
	v_mov_b32_e32 v72, v66
	v_mov_b32_e32 v73, v66
	v_mov_b32_e32 v74, v66
	v_mov_b32_e32 v75, v66
	v_mov_b32_e32 v76, v66
	v_mov_b32_e32 v77, v66
	v_mov_b32_e32 v78, v66
	v_mov_b32_e32 v79, v66
	v_mov_b32_e32 v80, v66
	v_mov_b32_e32 v81, v66
	v_sub_f32_e32 v142, v142, v90
	v_sub_f32_e32 v143, v143, v90
	v_sub_f32_e32 v144, v144, v90
	v_sub_f32_e32 v145, v145, v90
	v_sub_f32_e32 v146, v146, v90
	v_sub_f32_e32 v147, v147, v90
	v_sub_f32_e32 v148, v148, v90
	v_sub_f32_e32 v149, v149, v90
	v_sub_f32_e32 v150, v150, v90
	v_sub_f32_e32 v151, v151, v90
	v_sub_f32_e32 v152, v152, v90
	v_sub_f32_e32 v153, v153, v90
	v_sub_f32_e32 v154, v154, v90
	v_sub_f32_e32 v155, v155, v90
	v_sub_f32_e32 v156, v156, v90
	v_sub_f32_e32 v157, v157, v90
	v_sub_f32_e32 v158, v158, v90
	v_sub_f32_e32 v159, v159, v90
	v_sub_f32_e32 v160, v160, v90
	v_sub_f32_e32 v161, v161, v90
	v_sub_f32_e32 v162, v162, v90
	v_sub_f32_e32 v163, v163, v90
	v_sub_f32_e32 v164, v164, v90
	v_sub_f32_e32 v165, v165, v90
	v_sub_f32_e32 v166, v166, v90
	v_sub_f32_e32 v167, v167, v90
	v_sub_f32_e32 v168, v168, v90
	v_sub_f32_e32 v169, v169, v90
	v_sub_f32_e32 v170, v170, v90
	v_sub_f32_e32 v171, v171, v90
	v_sub_f32_e32 v172, v172, v90
	v_sub_f32_e32 v173, v173, v90
	v_mul_f32_e32 v236, v236, v91
	s_mov_b64 s[96:97], exec
	s_and_b64 exec, exec, s[8:9]
	ds_write_b32 v235, v91
	s_mov_b64 exec, s[96:97]
	v_lshl_add_u32 v2, v228, 4, s47
	ds_read_b128 v[94:97], v2 offset:0
	s_waitcnt lgkmcnt(0)
	v_mul_f32_e32 v34, v34, v94
	v_mul_f32_e32 v50, v50, v94
	v_mul_f32_e32 v35, v35, v95
	v_mul_f32_e32 v51, v51, v95
	v_mul_f32_e32 v36, v36, v96
	v_mul_f32_e32 v52, v52, v96
	v_mul_f32_e32 v37, v37, v97
	v_mul_f32_e32 v53, v53, v97
	ds_read_b128 v[94:97], v2 offset:32
	s_waitcnt lgkmcnt(0)
	v_mul_f32_e32 v38, v38, v94
	v_mul_f32_e32 v54, v54, v94
	v_mul_f32_e32 v39, v39, v95
	v_mul_f32_e32 v55, v55, v95
	v_mul_f32_e32 v40, v40, v96
	v_mul_f32_e32 v56, v56, v96
	v_mul_f32_e32 v41, v41, v97
	v_mul_f32_e32 v57, v57, v97
	ds_read_b128 v[94:97], v2 offset:64
	s_waitcnt lgkmcnt(0)
	v_mul_f32_e32 v42, v42, v94
	v_mul_f32_e32 v58, v58, v94
	v_mul_f32_e32 v43, v43, v95
	v_mul_f32_e32 v59, v59, v95
	v_mul_f32_e32 v44, v44, v96
	v_mul_f32_e32 v60, v60, v96
	v_mul_f32_e32 v45, v45, v97
	v_mul_f32_e32 v61, v61, v97
	ds_read_b128 v[94:97], v2 offset:96
	s_waitcnt lgkmcnt(0)
	v_mul_f32_e32 v46, v46, v94
	v_mul_f32_e32 v62, v62, v94
	v_mul_f32_e32 v47, v47, v95
	v_mul_f32_e32 v63, v63, v95
	v_mul_f32_e32 v48, v48, v96
	v_mul_f32_e32 v64, v64, v96
	v_mul_f32_e32 v49, v49, v97
	v_mul_f32_e32 v65, v65, v97
